# re-measure of the version with SP2 DMA-first and SP1 DMAs ahead of the read wait (noise check)
# baseline (speedup 1.0000x reference)
.LBB0_318:
	v_add_u32_e32 v128, 0x10000, v251
	ds_read_b128 v[146:149], v128
	ds_read_b128 v[150:153], v128 offset:1024
	ds_read_b128 v[154:157], v128 offset:2048
	ds_read_b128 v[158:161], v128 offset:3072
	v_add_u32_e32 v128, 0x14000, v251
	ds_read_b128 v[130:133], v128
	ds_read_b128 v[134:137], v128 offset:1024
	ds_read_b128 v[138:141], v128 offset:2048
	ds_read_b128 v[142:145], v128 offset:3072
	s_add_u32 s42, s93, s9
	s_addc_u32 s43, s94, 0
	s_add_u32 s42, s42, 0xffffff80
	s_addc_u32 s43, s43, -1
	s_mov_b32 s74, m0
	s_mov_b32 m0, s65
	s_nop 0
	global_load_lds_dwordx4 v245, s[42:43]
	s_mov_b32 m0, s74
	s_nop 0
	s_mov_b32 s74, m0
	s_mov_b32 m0, s66
	s_nop 0
	global_load_lds_dwordx4 v247, s[42:43]
	s_mov_b32 m0, s74
	s_cmp_eq_u32 s57, s3
	s_cselect_b32 s73, s55, s94
	s_cselect_b32 s72, s54, s93
	s_cselect_b32 s77, s63, s92
	s_cselect_b32 s76, s62, s8
	s_waitcnt lgkmcnt(0)
	ds_read_b128 v[162:165], v252
	ds_read_b128 v[166:169], v252 offset:1024
	ds_read_b128 v[170:173], v252 offset:2048
	ds_read_b128 v[174:177], v252 offset:3072
	ds_read_b128 v[178:181], v252 offset:4096
	ds_read_b128 v[182:185], v252 offset:5120
	ds_read_b128 v[186:189], v252 offset:6144
	ds_read_b128 v[190:193], v252 offset:7168
	s_waitcnt vmcnt(8)
	s_waitcnt lgkmcnt(0)
	s_barrier
	s_setprio 1
	s_waitcnt lgkmcnt(0)
	v_mfma_f32_16x16x32_bf16 v[124:127], v[146:149], v[162:165], v[124:127]
	v_mfma_f32_16x16x32_bf16 v[120:123], v[154:157], v[162:165], v[120:123]
	v_mfma_f32_16x16x32_bf16 v[108:111], v[146:149], v[170:173], v[108:111]
	v_mfma_f32_16x16x32_bf16 v[104:107], v[154:157], v[170:173], v[104:107]
	v_mfma_f32_16x16x32_bf16 v[92:95], v[146:149], v[178:181], v[92:95]
	v_mfma_f32_16x16x32_bf16 v[88:91], v[154:157], v[178:181], v[88:91]
	v_mfma_f32_16x16x32_bf16 v[76:79], v[146:149], v[186:189], v[76:79]
	v_mfma_f32_16x16x32_bf16 v[72:75], v[154:157], v[186:189], v[72:75]
	v_mfma_f32_16x16x32_bf16 v[124:127], v[150:153], v[166:169], v[124:127]
	v_mfma_f32_16x16x32_bf16 v[120:123], v[158:161], v[166:169], v[120:123]
	v_mfma_f32_16x16x32_bf16 v[108:111], v[150:153], v[174:177], v[108:111]
	v_mfma_f32_16x16x32_bf16 v[104:107], v[158:161], v[174:177], v[104:107]
	v_mfma_f32_16x16x32_bf16 v[92:95], v[150:153], v[182:185], v[92:95]
	v_mfma_f32_16x16x32_bf16 v[88:91], v[158:161], v[182:185], v[88:91]
	v_mfma_f32_16x16x32_bf16 v[76:79], v[150:153], v[190:193], v[76:79]
	v_mfma_f32_16x16x32_bf16 v[72:75], v[158:161], v[190:193], v[72:75]
	s_setprio 0
	s_setprio 1
	v_mfma_f32_16x16x32_bf16 v[116:119], v[130:133], v[162:165], v[116:119]
	v_mfma_f32_16x16x32_bf16 v[112:115], v[138:141], v[162:165], v[112:115]
	v_mfma_f32_16x16x32_bf16 v[100:103], v[130:133], v[170:173], v[100:103]
	v_mfma_f32_16x16x32_bf16 v[96:99], v[138:141], v[170:173], v[96:99]
	v_mfma_f32_16x16x32_bf16 v[84:87], v[130:133], v[178:181], v[84:87]
	v_mfma_f32_16x16x32_bf16 v[80:83], v[138:141], v[178:181], v[80:83]
	v_mfma_f32_16x16x32_bf16 v[68:71], v[130:133], v[186:189], v[68:71]
	v_mfma_f32_16x16x32_bf16 v[64:67], v[138:141], v[186:189], v[64:67]
	v_mfma_f32_16x16x32_bf16 v[116:119], v[134:137], v[166:169], v[116:119]
	v_mfma_f32_16x16x32_bf16 v[112:115], v[142:145], v[166:169], v[112:115]
	v_mfma_f32_16x16x32_bf16 v[100:103], v[134:137], v[174:177], v[100:103]
	v_mfma_f32_16x16x32_bf16 v[96:99], v[142:145], v[174:177], v[96:99]
	v_mfma_f32_16x16x32_bf16 v[84:87], v[134:137], v[182:185], v[84:87]
	v_mfma_f32_16x16x32_bf16 v[80:83], v[142:145], v[182:185], v[80:83]
	v_mfma_f32_16x16x32_bf16 v[68:71], v[134:137], v[190:193], v[68:71]
	v_mfma_f32_16x16x32_bf16 v[64:67], v[142:145], v[190:193], v[64:67]
	s_setprio 0
	s_barrier
	s_mov_b32 s42, m0
	s_mov_b32 m0, s14
	s_nop 0
	global_load_lds_dwordx4 v246, s[76:77]
	s_mov_b32 m0, s42
	s_add_u32 s74, s76, s9
	s_mov_b32 s42, m0
	s_mov_b32 m0, s15
	s_nop 0
	global_load_lds_dwordx4 v248, s[76:77]
	s_mov_b32 m0, s42
	s_addc_u32 s75, s77, 0
	s_mov_b32 s42, m0
	s_mov_b32 m0, s16
	s_nop 0
	global_load_lds_dwordx4 v246, s[74:75]
	s_mov_b32 m0, s42
	v_cndmask_b32_e64 v128, 0, 1, s[68:69]
	s_mov_b32 s42, m0
	s_mov_b32 m0, s17
	s_nop 0
	global_load_lds_dwordx4 v248, s[74:75]
	s_mov_b32 m0, s42
	s_andn2_b64 vcc, exec, s[68:69]
	s_mov_b32 s42, m0
	s_mov_b32 m0, s11
	s_nop 0
	global_load_lds_dwordx4 v245, s[72:73]
	s_mov_b32 m0, s42
	s_nop 0
	s_mov_b32 s42, m0
	s_mov_b32 m0, s19
	s_nop 0
	global_load_lds_dwordx4 v247, s[72:73]
	s_mov_b32 m0, s42
	ds_read_b128 v[186:189], v252 offset:16384
	ds_read_b128 v[190:193], v252 offset:17408
	ds_read_b128 v[178:181], v252 offset:18432
	ds_read_b128 v[182:185], v252 offset:19456
	ds_read_b128 v[170:173], v252 offset:20480
	ds_read_b128 v[174:177], v252 offset:21504
	ds_read_b128 v[162:165], v252 offset:22528
	ds_read_b128 v[166:169], v252 offset:23552
	s_waitcnt vmcnt(8)
	s_waitcnt lgkmcnt(0)
	s_barrier
	v_cmp_ne_u32_e64 s[42:43], 1, v128
	s_cbranch_vccnz .LBB0_320
	s_setprio 1
	s_waitcnt lgkmcnt(0)
	v_mfma_f32_16x16x32_bf16 v[60:63], v[146:149], v[186:189], v[60:63]
	v_mfma_f32_16x16x32_bf16 v[56:59], v[154:157], v[186:189], v[56:59]
	v_mfma_f32_16x16x32_bf16 v[44:47], v[146:149], v[178:181], v[44:47]
	v_mfma_f32_16x16x32_bf16 v[40:43], v[154:157], v[178:181], v[40:43]
	v_mfma_f32_16x16x32_bf16 v[28:31], v[146:149], v[170:173], v[28:31]
	v_mfma_f32_16x16x32_bf16 v[24:27], v[154:157], v[170:173], v[24:27]
	v_mfma_f32_16x16x32_bf16 v[12:15], v[146:149], v[162:165], v[12:15]
	v_mfma_f32_16x16x32_bf16 v[8:11], v[154:157], v[162:165], v[8:11]
	v_mfma_f32_16x16x32_bf16 v[60:63], v[150:153], v[190:193], v[60:63]
	v_mfma_f32_16x16x32_bf16 v[56:59], v[158:161], v[190:193], v[56:59]
	v_mfma_f32_16x16x32_bf16 v[44:47], v[150:153], v[182:185], v[44:47]
	v_mfma_f32_16x16x32_bf16 v[40:43], v[158:161], v[182:185], v[40:43]
	v_mfma_f32_16x16x32_bf16 v[28:31], v[150:153], v[174:177], v[28:31]
	v_mfma_f32_16x16x32_bf16 v[24:27], v[158:161], v[174:177], v[24:27]
	v_mfma_f32_16x16x32_bf16 v[12:15], v[150:153], v[166:169], v[12:15]
	v_mfma_f32_16x16x32_bf16 v[8:11], v[158:161], v[166:169], v[8:11]
	s_setprio 0
	s_setprio 1
	v_mfma_f32_16x16x32_bf16 v[52:55], v[130:133], v[186:189], v[52:55]
	v_mfma_f32_16x16x32_bf16 v[48:51], v[138:141], v[186:189], v[48:51]
	v_mfma_f32_16x16x32_bf16 v[36:39], v[130:133], v[178:181], v[36:39]
	v_mfma_f32_16x16x32_bf16 v[32:35], v[138:141], v[178:181], v[32:35]
	v_mfma_f32_16x16x32_bf16 v[20:23], v[130:133], v[170:173], v[20:23]
	v_mfma_f32_16x16x32_bf16 v[16:19], v[138:141], v[170:173], v[16:19]
	v_mfma_f32_16x16x32_bf16 v[4:7], v[130:133], v[162:165], v[4:7]
	v_mfma_f32_16x16x32_bf16 v[0:3], v[138:141], v[162:165], v[0:3]
	v_mfma_f32_16x16x32_bf16 v[52:55], v[134:137], v[190:193], v[52:55]
	v_mfma_f32_16x16x32_bf16 v[48:51], v[142:145], v[190:193], v[48:51]
	v_mfma_f32_16x16x32_bf16 v[36:39], v[134:137], v[182:185], v[36:39]
	v_mfma_f32_16x16x32_bf16 v[32:35], v[142:145], v[182:185], v[32:35]
	v_mfma_f32_16x16x32_bf16 v[20:23], v[134:137], v[174:177], v[20:23]
	v_mfma_f32_16x16x32_bf16 v[16:19], v[142:145], v[174:177], v[16:19]
	v_mfma_f32_16x16x32_bf16 v[4:7], v[134:137], v[166:169], v[4:7]
	v_mfma_f32_16x16x32_bf16 v[0:3], v[142:145], v[166:169], v[0:3]
	s_setprio 0
.LBB0_320:
	s_add_u32 s80, s72, 0x80
	s_addc_u32 s81, s73, 0
	s_add_u32 s76, s76, 0x80
	s_addc_u32 s77, s77, 0
	s_barrier
	v_add_u32_e32 v128, 0x18000, v251
	ds_read_b128 v[146:149], v128
	ds_read_b128 v[150:153], v128 offset:1024
	ds_read_b128 v[154:157], v128 offset:2048
	ds_read_b128 v[158:161], v128 offset:3072
	v_add_u32_e32 v128, 0x1c000, v251
	ds_read_b128 v[130:133], v128
	ds_read_b128 v[134:137], v128 offset:1024
	ds_read_b128 v[138:141], v128 offset:2048
	ds_read_b128 v[142:145], v128 offset:3072
	s_add_u32 s72, s72, s9
	s_addc_u32 s73, s73, 0
	s_mov_b32 s95, m0
	s_mov_b32 m0, s20
	s_nop 0
	global_load_lds_dwordx4 v245, s[72:73]
	s_mov_b32 m0, s95
	s_nop 0
	s_mov_b32 s95, m0
	s_mov_b32 m0, s21
	s_nop 0
	global_load_lds_dwordx4 v247, s[72:73]
	s_mov_b32 m0, s95
	s_waitcnt lgkmcnt(0)
	ds_read_b128 v[162:165], v252 offset:32768
	ds_read_b128 v[166:169], v252 offset:33792
	ds_read_b128 v[170:173], v252 offset:34816
	ds_read_b128 v[174:177], v252 offset:35840
	ds_read_b128 v[178:181], v252 offset:36864
	ds_read_b128 v[182:185], v252 offset:37888
	ds_read_b128 v[186:189], v252 offset:38912
	ds_read_b128 v[190:193], v252 offset:39936
	s_waitcnt vmcnt(8)
	s_waitcnt lgkmcnt(0)
	s_barrier
	s_setprio 1
	s_waitcnt lgkmcnt(0)
	v_mfma_f32_16x16x32_bf16 v[124:127], v[146:149], v[162:165], v[124:127]
	v_mfma_f32_16x16x32_bf16 v[120:123], v[154:157], v[162:165], v[120:123]
	v_mfma_f32_16x16x32_bf16 v[108:111], v[146:149], v[170:173], v[108:111]
	v_mfma_f32_16x16x32_bf16 v[104:107], v[154:157], v[170:173], v[104:107]
	v_mfma_f32_16x16x32_bf16 v[92:95], v[146:149], v[178:181], v[92:95]
	v_mfma_f32_16x16x32_bf16 v[88:91], v[154:157], v[178:181], v[88:91]
	v_mfma_f32_16x16x32_bf16 v[76:79], v[146:149], v[186:189], v[76:79]
	v_mfma_f32_16x16x32_bf16 v[72:75], v[154:157], v[186:189], v[72:75]
	v_mfma_f32_16x16x32_bf16 v[124:127], v[150:153], v[166:169], v[124:127]
	v_mfma_f32_16x16x32_bf16 v[120:123], v[158:161], v[166:169], v[120:123]
	v_mfma_f32_16x16x32_bf16 v[108:111], v[150:153], v[174:177], v[108:111]
	v_mfma_f32_16x16x32_bf16 v[104:107], v[158:161], v[174:177], v[104:107]
	v_mfma_f32_16x16x32_bf16 v[92:95], v[150:153], v[182:185], v[92:95]
	v_mfma_f32_16x16x32_bf16 v[88:91], v[158:161], v[182:185], v[88:91]
	v_mfma_f32_16x16x32_bf16 v[76:79], v[150:153], v[190:193], v[76:79]
	v_mfma_f32_16x16x32_bf16 v[72:75], v[158:161], v[190:193], v[72:75]
	s_setprio 0
	s_setprio 1
	v_mfma_f32_16x16x32_bf16 v[116:119], v[130:133], v[162:165], v[116:119]
	v_mfma_f32_16x16x32_bf16 v[112:115], v[138:141], v[162:165], v[112:115]
	v_mfma_f32_16x16x32_bf16 v[100:103], v[130:133], v[170:173], v[100:103]
	v_mfma_f32_16x16x32_bf16 v[96:99], v[138:141], v[170:173], v[96:99]
	v_mfma_f32_16x16x32_bf16 v[84:87], v[130:133], v[178:181], v[84:87]
	v_mfma_f32_16x16x32_bf16 v[80:83], v[138:141], v[178:181], v[80:83]
	v_mfma_f32_16x16x32_bf16 v[68:71], v[130:133], v[186:189], v[68:71]
	v_mfma_f32_16x16x32_bf16 v[64:67], v[138:141], v[186:189], v[64:67]
	v_mfma_f32_16x16x32_bf16 v[116:119], v[134:137], v[166:169], v[116:119]
	v_mfma_f32_16x16x32_bf16 v[112:115], v[142:145], v[166:169], v[112:115]
	v_mfma_f32_16x16x32_bf16 v[100:103], v[134:137], v[174:177], v[100:103]
	v_mfma_f32_16x16x32_bf16 v[96:99], v[142:145], v[174:177], v[96:99]
	v_mfma_f32_16x16x32_bf16 v[84:87], v[134:137], v[182:185], v[84:87]
	v_mfma_f32_16x16x32_bf16 v[80:83], v[142:145], v[182:185], v[80:83]
	v_mfma_f32_16x16x32_bf16 v[68:71], v[134:137], v[190:193], v[68:71]
	v_mfma_f32_16x16x32_bf16 v[64:67], v[142:145], v[190:193], v[64:67]
	s_setprio 0
	s_barrier
	s_mov_b32 s72, m0
	s_mov_b32 m0, s23
	s_nop 0
	global_load_lds_dwordx4 v246, s[76:77]
	s_mov_b32 m0, s72
	s_nop 0
	s_mov_b32 s72, m0
	s_mov_b32 m0, s30
	s_nop 0
	global_load_lds_dwordx4 v248, s[76:77]
	s_mov_b32 m0, s72
	s_add_u32 s72, s74, 0x80
	s_addc_u32 s73, s75, 0
	s_mov_b32 s74, m0
	s_mov_b32 m0, s52
	s_nop 0
	global_load_lds_dwordx4 v246, s[72:73]
	s_mov_b32 m0, s74
	s_and_b64 vcc, exec, s[42:43]
	s_mov_b32 s74, m0
	s_mov_b32 m0, s53
	s_nop 0
	global_load_lds_dwordx4 v248, s[72:73]
	s_mov_b32 m0, s74
	s_mov_b32 s72, m0
	s_mov_b32 m0, s47
	s_nop 0
	global_load_lds_dwordx4 v245, s[80:81]
	s_mov_b32 m0, s72
	s_nop 0
	s_mov_b32 s72, m0
	s_mov_b32 m0, s50
	s_nop 0
	global_load_lds_dwordx4 v247, s[80:81]
	s_mov_b32 m0, s72
	ds_read_b128 v[186:189], v252 offset:49152
	ds_read_b128 v[190:193], v252 offset:50176
	ds_read_b128 v[178:181], v252 offset:51200
	ds_read_b128 v[182:185], v252 offset:52224
	ds_read_b128 v[170:173], v252 offset:53248
	ds_read_b128 v[174:177], v252 offset:54272
	ds_read_b128 v[162:165], v252 offset:55296
	ds_read_b128 v[166:169], v252 offset:56320
	s_waitcnt vmcnt(8)
	s_waitcnt lgkmcnt(0)
	s_barrier
	s_cbranch_vccnz .LBB0_317
	s_setprio 1
	s_waitcnt lgkmcnt(0)
	v_mfma_f32_16x16x32_bf16 v[60:63], v[146:149], v[186:189], v[60:63]
	v_mfma_f32_16x16x32_bf16 v[56:59], v[154:157], v[186:189], v[56:59]
	v_mfma_f32_16x16x32_bf16 v[44:47], v[146:149], v[178:181], v[44:47]
	v_mfma_f32_16x16x32_bf16 v[40:43], v[154:157], v[178:181], v[40:43]
	v_mfma_f32_16x16x32_bf16 v[28:31], v[146:149], v[170:173], v[28:31]
	v_mfma_f32_16x16x32_bf16 v[24:27], v[154:157], v[170:173], v[24:27]
	v_mfma_f32_16x16x32_bf16 v[12:15], v[146:149], v[162:165], v[12:15]
	v_mfma_f32_16x16x32_bf16 v[8:11], v[154:157], v[162:165], v[8:11]
	v_mfma_f32_16x16x32_bf16 v[60:63], v[150:153], v[190:193], v[60:63]
	v_mfma_f32_16x16x32_bf16 v[56:59], v[158:161], v[190:193], v[56:59]
	v_mfma_f32_16x16x32_bf16 v[44:47], v[150:153], v[182:185], v[44:47]
	v_mfma_f32_16x16x32_bf16 v[40:43], v[158:161], v[182:185], v[40:43]
	v_mfma_f32_16x16x32_bf16 v[28:31], v[150:153], v[174:177], v[28:31]
	v_mfma_f32_16x16x32_bf16 v[24:27], v[158:161], v[174:177], v[24:27]
	v_mfma_f32_16x16x32_bf16 v[12:15], v[150:153], v[166:169], v[12:15]
	v_mfma_f32_16x16x32_bf16 v[8:11], v[158:161], v[166:169], v[8:11]
	s_setprio 0
	s_setprio 1
	v_mfma_f32_16x16x32_bf16 v[52:55], v[130:133], v[186:189], v[52:55]
	v_mfma_f32_16x16x32_bf16 v[48:51], v[138:141], v[186:189], v[48:51]
	v_mfma_f32_16x16x32_bf16 v[36:39], v[130:133], v[178:181], v[36:39]
	v_mfma_f32_16x16x32_bf16 v[32:35], v[138:141], v[178:181], v[32:35]
	v_mfma_f32_16x16x32_bf16 v[20:23], v[130:133], v[170:173], v[20:23]
	v_mfma_f32_16x16x32_bf16 v[16:19], v[138:141], v[170:173], v[16:19]
	v_mfma_f32_16x16x32_bf16 v[4:7], v[130:133], v[162:165], v[4:7]
	v_mfma_f32_16x16x32_bf16 v[0:3], v[138:141], v[162:165], v[0:3]
	v_mfma_f32_16x16x32_bf16 v[52:55], v[134:137], v[190:193], v[52:55]
	v_mfma_f32_16x16x32_bf16 v[48:51], v[142:145], v[190:193], v[48:51]
	v_mfma_f32_16x16x32_bf16 v[36:39], v[134:137], v[182:185], v[36:39]
	v_mfma_f32_16x16x32_bf16 v[32:35], v[142:145], v[182:185], v[32:35]
	v_mfma_f32_16x16x32_bf16 v[20:23], v[134:137], v[174:177], v[20:23]
	v_mfma_f32_16x16x32_bf16 v[16:19], v[142:145], v[174:177], v[16:19]
	v_mfma_f32_16x16x32_bf16 v[4:7], v[134:137], v[166:169], v[4:7]
	v_mfma_f32_16x16x32_bf16 v[0:3], v[142:145], v[166:169], v[0:3]
	s_setprio 0
	s_branch .LBB0_317

.LBB0_413:
	v_add_u32_e32 v128, 0x10000, v208
	ds_read_b128 v[146:149], v128
	ds_read_b128 v[150:153], v128 offset:1024
	ds_read_b128 v[154:157], v128 offset:2048
	ds_read_b128 v[158:161], v128 offset:3072
	v_add_u32_e32 v128, 0x14000, v208
	ds_read_b128 v[130:133], v128
	ds_read_b128 v[134:137], v128 offset:1024
	ds_read_b128 v[138:141], v128 offset:2048
	ds_read_b128 v[142:145], v128 offset:3072
	s_mov_b32 s38, m0
	s_mov_b32 m0, s30
	s_nop 0
	global_load_lds_dwordx4 v195, s[46:47]
	s_mov_b32 m0, s38
	s_nop 0
	s_mov_b32 s38, m0
	s_mov_b32 m0, s14
	s_nop 0
	global_load_lds_dwordx4 v197, s[46:47]
	s_mov_b32 m0, s38
	s_add_u32 s38, s46, 0xfffc0080
	s_addc_u32 s39, s47, -1
	s_cmp_eq_u32 s19, 12
	s_cselect_b32 s75, s27, s39
	s_cselect_b32 s74, s99, s38
	s_cselect_b32 s63, s23, s18
	s_cselect_b32 s62, s3, s8
	s_waitcnt lgkmcnt(0)
	ds_read_b128 v[162:165], v209
	ds_read_b128 v[166:169], v209 offset:1024
	ds_read_b128 v[170:173], v209 offset:2048
	ds_read_b128 v[174:177], v209 offset:3072
	ds_read_b128 v[178:181], v209 offset:4096
	ds_read_b128 v[182:185], v209 offset:5120
	ds_read_b128 v[186:189], v209 offset:6144
	ds_read_b128 v[190:193], v209 offset:7168
	s_waitcnt vmcnt(8)
	s_waitcnt lgkmcnt(0)
	s_barrier
	s_setprio 1
	s_waitcnt lgkmcnt(0)
	v_mfma_f32_16x16x32_bf16 v[124:127], v[146:149], v[162:165], v[124:127]
	v_mfma_f32_16x16x32_bf16 v[120:123], v[154:157], v[162:165], v[120:123]
	v_mfma_f32_16x16x32_bf16 v[108:111], v[146:149], v[170:173], v[108:111]
	v_mfma_f32_16x16x32_bf16 v[104:107], v[154:157], v[170:173], v[104:107]
	v_mfma_f32_16x16x32_bf16 v[92:95], v[146:149], v[178:181], v[92:95]
	v_mfma_f32_16x16x32_bf16 v[88:91], v[154:157], v[178:181], v[88:91]
	v_mfma_f32_16x16x32_bf16 v[76:79], v[146:149], v[186:189], v[76:79]
	v_mfma_f32_16x16x32_bf16 v[72:75], v[154:157], v[186:189], v[72:75]
	v_mfma_f32_16x16x32_bf16 v[124:127], v[150:153], v[166:169], v[124:127]
	v_mfma_f32_16x16x32_bf16 v[120:123], v[158:161], v[166:169], v[120:123]
	v_mfma_f32_16x16x32_bf16 v[108:111], v[150:153], v[174:177], v[108:111]
	v_mfma_f32_16x16x32_bf16 v[104:107], v[158:161], v[174:177], v[104:107]
	v_mfma_f32_16x16x32_bf16 v[92:95], v[150:153], v[182:185], v[92:95]
	v_mfma_f32_16x16x32_bf16 v[88:91], v[158:161], v[182:185], v[88:91]
	v_mfma_f32_16x16x32_bf16 v[76:79], v[150:153], v[190:193], v[76:79]
	v_mfma_f32_16x16x32_bf16 v[72:75], v[158:161], v[190:193], v[72:75]
	s_setprio 0
	s_setprio 1
	v_mfma_f32_16x16x32_bf16 v[116:119], v[130:133], v[162:165], v[116:119]
	v_mfma_f32_16x16x32_bf16 v[112:115], v[138:141], v[162:165], v[112:115]
	v_mfma_f32_16x16x32_bf16 v[100:103], v[130:133], v[170:173], v[100:103]
	v_mfma_f32_16x16x32_bf16 v[96:99], v[138:141], v[170:173], v[96:99]
	v_mfma_f32_16x16x32_bf16 v[84:87], v[130:133], v[178:181], v[84:87]
	v_mfma_f32_16x16x32_bf16 v[80:83], v[138:141], v[178:181], v[80:83]
	v_mfma_f32_16x16x32_bf16 v[68:71], v[130:133], v[186:189], v[68:71]
	v_mfma_f32_16x16x32_bf16 v[64:67], v[138:141], v[186:189], v[64:67]
	v_mfma_f32_16x16x32_bf16 v[116:119], v[134:137], v[166:169], v[116:119]
	v_mfma_f32_16x16x32_bf16 v[112:115], v[142:145], v[166:169], v[112:115]
	v_mfma_f32_16x16x32_bf16 v[100:103], v[134:137], v[174:177], v[100:103]
	v_mfma_f32_16x16x32_bf16 v[96:99], v[142:145], v[174:177], v[96:99]
	v_mfma_f32_16x16x32_bf16 v[84:87], v[134:137], v[182:185], v[84:87]
	v_mfma_f32_16x16x32_bf16 v[80:83], v[142:145], v[182:185], v[80:83]
	v_mfma_f32_16x16x32_bf16 v[68:71], v[134:137], v[190:193], v[68:71]
	v_mfma_f32_16x16x32_bf16 v[64:67], v[142:145], v[190:193], v[64:67]
	s_setprio 0
	s_barrier
	s_mov_b32 s38, m0
	s_mov_b32 m0, s67
	s_nop 0
	global_load_lds_dwordx4 v196, s[62:63]
	s_mov_b32 m0, s38
	s_add_u32 s44, s62, 0x40000
	s_mov_b32 s38, m0
	s_mov_b32 m0, s86
	s_nop 0
	global_load_lds_dwordx4 v198, s[62:63]
	s_mov_b32 m0, s38
	s_addc_u32 s45, s63, 0
	s_mov_b32 s38, m0
	s_mov_b32 m0, s87
	s_nop 0
	global_load_lds_dwordx4 v196, s[44:45]
	s_mov_b32 m0, s38
	v_cndmask_b32_e64 v128, 0, 1, s[72:73]
	s_mov_b32 s38, m0
	s_mov_b32 m0, s88
	s_nop 0
	global_load_lds_dwordx4 v198, s[44:45]
	s_mov_b32 m0, s38
	v_cmp_ne_u32_e64 s[44:45], 1, v128
	s_mov_b32 s38, m0
	s_mov_b32 m0, s51
	s_nop 0
	global_load_lds_dwordx4 v195, s[74:75]
	s_mov_b32 m0, s38
	s_andn2_b64 vcc, exec, s[72:73]
	s_mov_b32 s38, m0
	s_mov_b32 m0, s89
	s_nop 0
	global_load_lds_dwordx4 v197, s[74:75]
	s_mov_b32 m0, s38
	ds_read_b128 v[186:189], v209 offset:16384
	ds_read_b128 v[190:193], v209 offset:17408
	ds_read_b128 v[178:181], v209 offset:18432
	ds_read_b128 v[182:185], v209 offset:19456
	ds_read_b128 v[170:173], v209 offset:20480
	ds_read_b128 v[174:177], v209 offset:21504
	ds_read_b128 v[162:165], v209 offset:22528
	ds_read_b128 v[166:169], v209 offset:23552
	s_waitcnt vmcnt(8)
	s_waitcnt lgkmcnt(0)
	s_barrier
	s_cbranch_vccnz .LBB0_415
	s_setprio 1
	s_waitcnt lgkmcnt(0)
	v_mfma_f32_16x16x32_bf16 v[60:63], v[146:149], v[186:189], v[60:63]
	v_mfma_f32_16x16x32_bf16 v[56:59], v[154:157], v[186:189], v[56:59]
	v_mfma_f32_16x16x32_bf16 v[44:47], v[146:149], v[178:181], v[44:47]
	v_mfma_f32_16x16x32_bf16 v[40:43], v[154:157], v[178:181], v[40:43]
	v_mfma_f32_16x16x32_bf16 v[28:31], v[146:149], v[170:173], v[28:31]
	v_mfma_f32_16x16x32_bf16 v[24:27], v[154:157], v[170:173], v[24:27]
	v_mfma_f32_16x16x32_bf16 v[12:15], v[146:149], v[162:165], v[12:15]
	v_mfma_f32_16x16x32_bf16 v[8:11], v[154:157], v[162:165], v[8:11]
	v_mfma_f32_16x16x32_bf16 v[60:63], v[150:153], v[190:193], v[60:63]
	v_mfma_f32_16x16x32_bf16 v[56:59], v[158:161], v[190:193], v[56:59]
	v_mfma_f32_16x16x32_bf16 v[44:47], v[150:153], v[182:185], v[44:47]
	v_mfma_f32_16x16x32_bf16 v[40:43], v[158:161], v[182:185], v[40:43]
	v_mfma_f32_16x16x32_bf16 v[28:31], v[150:153], v[174:177], v[28:31]
	v_mfma_f32_16x16x32_bf16 v[24:27], v[158:161], v[174:177], v[24:27]
	v_mfma_f32_16x16x32_bf16 v[12:15], v[150:153], v[166:169], v[12:15]
	v_mfma_f32_16x16x32_bf16 v[8:11], v[158:161], v[166:169], v[8:11]
	s_setprio 0
	s_setprio 1
	v_mfma_f32_16x16x32_bf16 v[52:55], v[130:133], v[186:189], v[52:55]
	v_mfma_f32_16x16x32_bf16 v[48:51], v[138:141], v[186:189], v[48:51]
	v_mfma_f32_16x16x32_bf16 v[36:39], v[130:133], v[178:181], v[36:39]
	v_mfma_f32_16x16x32_bf16 v[32:35], v[138:141], v[178:181], v[32:35]
	v_mfma_f32_16x16x32_bf16 v[20:23], v[130:133], v[170:173], v[20:23]
	v_mfma_f32_16x16x32_bf16 v[16:19], v[138:141], v[170:173], v[16:19]
	v_mfma_f32_16x16x32_bf16 v[4:7], v[130:133], v[162:165], v[4:7]
	v_mfma_f32_16x16x32_bf16 v[0:3], v[138:141], v[162:165], v[0:3]
	v_mfma_f32_16x16x32_bf16 v[52:55], v[134:137], v[190:193], v[52:55]
	v_mfma_f32_16x16x32_bf16 v[48:51], v[142:145], v[190:193], v[48:51]
	v_mfma_f32_16x16x32_bf16 v[36:39], v[134:137], v[182:185], v[36:39]
	v_mfma_f32_16x16x32_bf16 v[32:35], v[142:145], v[182:185], v[32:35]
	v_mfma_f32_16x16x32_bf16 v[20:23], v[134:137], v[174:177], v[20:23]
	v_mfma_f32_16x16x32_bf16 v[16:19], v[142:145], v[174:177], v[16:19]
	v_mfma_f32_16x16x32_bf16 v[4:7], v[134:137], v[166:169], v[4:7]
	v_mfma_f32_16x16x32_bf16 v[0:3], v[142:145], v[166:169], v[0:3]
	s_setprio 0
.LBB0_415:
	s_add_u32 s76, s74, 0x80
	s_addc_u32 s77, s75, 0
	s_add_u32 s38, s62, 0x80
	s_addc_u32 s39, s63, 0
	s_barrier
	v_add_u32_e32 v128, 0x18000, v208
	ds_read_b128 v[146:149], v128
	ds_read_b128 v[150:153], v128 offset:1024
	ds_read_b128 v[154:157], v128 offset:2048
	ds_read_b128 v[158:161], v128 offset:3072
	v_add_u32_e32 v128, 0x1c000, v208
	ds_read_b128 v[130:133], v128
	ds_read_b128 v[134:137], v128 offset:1024
	ds_read_b128 v[138:141], v128 offset:2048
	ds_read_b128 v[142:145], v128 offset:3072
	s_add_u32 s74, s74, 0x40000
	s_addc_u32 s75, s75, 0
	s_mov_b32 vcc_lo, m0
	s_mov_b32 m0, s92
	s_nop 0
	global_load_lds_dwordx4 v195, s[74:75]
	s_mov_b32 m0, vcc_lo
	s_nop 0
	s_mov_b32 vcc_lo, m0
	s_mov_b32 m0, s93
	s_nop 0
	global_load_lds_dwordx4 v197, s[74:75]
	s_mov_b32 m0, vcc_lo
	s_waitcnt lgkmcnt(0)
	ds_read_b128 v[162:165], v209 offset:32768
	ds_read_b128 v[166:169], v209 offset:33792
	ds_read_b128 v[170:173], v209 offset:34816
	ds_read_b128 v[174:177], v209 offset:35840
	ds_read_b128 v[178:181], v209 offset:36864
	ds_read_b128 v[182:185], v209 offset:37888
	ds_read_b128 v[186:189], v209 offset:38912
	ds_read_b128 v[190:193], v209 offset:39936
	s_waitcnt vmcnt(8)
	s_waitcnt lgkmcnt(0)
	s_barrier
	s_setprio 1
	s_waitcnt lgkmcnt(0)
	v_mfma_f32_16x16x32_bf16 v[124:127], v[146:149], v[162:165], v[124:127]
	v_mfma_f32_16x16x32_bf16 v[120:123], v[154:157], v[162:165], v[120:123]
	v_mfma_f32_16x16x32_bf16 v[108:111], v[146:149], v[170:173], v[108:111]
	v_mfma_f32_16x16x32_bf16 v[104:107], v[154:157], v[170:173], v[104:107]
	v_mfma_f32_16x16x32_bf16 v[92:95], v[146:149], v[178:181], v[92:95]
	v_mfma_f32_16x16x32_bf16 v[88:91], v[154:157], v[178:181], v[88:91]
	v_mfma_f32_16x16x32_bf16 v[76:79], v[146:149], v[186:189], v[76:79]
	v_mfma_f32_16x16x32_bf16 v[72:75], v[154:157], v[186:189], v[72:75]
	v_mfma_f32_16x16x32_bf16 v[124:127], v[150:153], v[166:169], v[124:127]
	v_mfma_f32_16x16x32_bf16 v[120:123], v[158:161], v[166:169], v[120:123]
	v_mfma_f32_16x16x32_bf16 v[108:111], v[150:153], v[174:177], v[108:111]
	v_mfma_f32_16x16x32_bf16 v[104:107], v[158:161], v[174:177], v[104:107]
	v_mfma_f32_16x16x32_bf16 v[92:95], v[150:153], v[182:185], v[92:95]
	v_mfma_f32_16x16x32_bf16 v[88:91], v[158:161], v[182:185], v[88:91]
	v_mfma_f32_16x16x32_bf16 v[76:79], v[150:153], v[190:193], v[76:79]
	v_mfma_f32_16x16x32_bf16 v[72:75], v[158:161], v[190:193], v[72:75]
	s_setprio 0
	s_setprio 1
	v_mfma_f32_16x16x32_bf16 v[116:119], v[130:133], v[162:165], v[116:119]
	v_mfma_f32_16x16x32_bf16 v[112:115], v[138:141], v[162:165], v[112:115]
	v_mfma_f32_16x16x32_bf16 v[100:103], v[130:133], v[170:173], v[100:103]
	v_mfma_f32_16x16x32_bf16 v[96:99], v[138:141], v[170:173], v[96:99]
	v_mfma_f32_16x16x32_bf16 v[84:87], v[130:133], v[178:181], v[84:87]
	v_mfma_f32_16x16x32_bf16 v[80:83], v[138:141], v[178:181], v[80:83]
	v_mfma_f32_16x16x32_bf16 v[68:71], v[130:133], v[186:189], v[68:71]
	v_mfma_f32_16x16x32_bf16 v[64:67], v[138:141], v[186:189], v[64:67]
	v_mfma_f32_16x16x32_bf16 v[116:119], v[134:137], v[166:169], v[116:119]
	v_mfma_f32_16x16x32_bf16 v[112:115], v[142:145], v[166:169], v[112:115]
	v_mfma_f32_16x16x32_bf16 v[100:103], v[134:137], v[174:177], v[100:103]
	v_mfma_f32_16x16x32_bf16 v[96:99], v[142:145], v[174:177], v[96:99]
	v_mfma_f32_16x16x32_bf16 v[84:87], v[134:137], v[182:185], v[84:87]
	v_mfma_f32_16x16x32_bf16 v[80:83], v[142:145], v[182:185], v[80:83]
	v_mfma_f32_16x16x32_bf16 v[68:71], v[134:137], v[190:193], v[68:71]
	v_mfma_f32_16x16x32_bf16 v[64:67], v[142:145], v[190:193], v[64:67]
	s_setprio 0
	s_barrier
	s_mov_b32 s74, m0
	s_mov_b32 m0, s95
	s_nop 0
	global_load_lds_dwordx4 v196, s[38:39]
	s_mov_b32 m0, s74
	s_nop 0
	s_mov_b32 s74, m0
	s_mov_b32 m0, s96
	s_nop 0
	global_load_lds_dwordx4 v198, s[38:39]
	s_mov_b32 m0, s74
	s_add_u32 s38, s62, 0x40080
	s_addc_u32 s39, s63, 0
	s_mov_b32 s62, m0
	s_mov_b32 m0, s65
	s_nop 0
	global_load_lds_dwordx4 v196, s[38:39]
	s_mov_b32 m0, s62
	s_and_b64 vcc, exec, s[44:45]
	s_mov_b32 s62, m0
	s_mov_b32 m0, s50
	s_nop 0
	global_load_lds_dwordx4 v198, s[38:39]
	s_mov_b32 m0, s62
	s_mov_b32 s38, m0
	s_mov_b32 m0, s97
	s_nop 0
	global_load_lds_dwordx4 v195, s[76:77]
	s_mov_b32 m0, s38
	s_nop 0
	s_mov_b32 s38, m0
	s_mov_b32 m0, s9
	s_nop 0
	global_load_lds_dwordx4 v197, s[76:77]
	s_mov_b32 m0, s38
	ds_read_b128 v[186:189], v209 offset:49152
	ds_read_b128 v[190:193], v209 offset:50176
	ds_read_b128 v[178:181], v209 offset:51200
	ds_read_b128 v[182:185], v209 offset:52224
	ds_read_b128 v[170:173], v209 offset:53248
	ds_read_b128 v[174:177], v209 offset:54272
	ds_read_b128 v[162:165], v209 offset:55296
	ds_read_b128 v[166:169], v209 offset:56320
	s_waitcnt vmcnt(8)
	s_waitcnt lgkmcnt(0)
	s_barrier
	s_cbranch_vccnz .LBB0_412
	s_setprio 1
	s_waitcnt lgkmcnt(0)
	v_mfma_f32_16x16x32_bf16 v[60:63], v[146:149], v[186:189], v[60:63]
	v_mfma_f32_16x16x32_bf16 v[56:59], v[154:157], v[186:189], v[56:59]
	v_mfma_f32_16x16x32_bf16 v[44:47], v[146:149], v[178:181], v[44:47]
	v_mfma_f32_16x16x32_bf16 v[40:43], v[154:157], v[178:181], v[40:43]
	v_mfma_f32_16x16x32_bf16 v[28:31], v[146:149], v[170:173], v[28:31]
	v_mfma_f32_16x16x32_bf16 v[24:27], v[154:157], v[170:173], v[24:27]
	v_mfma_f32_16x16x32_bf16 v[12:15], v[146:149], v[162:165], v[12:15]
	v_mfma_f32_16x16x32_bf16 v[8:11], v[154:157], v[162:165], v[8:11]
	v_mfma_f32_16x16x32_bf16 v[60:63], v[150:153], v[190:193], v[60:63]
	v_mfma_f32_16x16x32_bf16 v[56:59], v[158:161], v[190:193], v[56:59]
	v_mfma_f32_16x16x32_bf16 v[44:47], v[150:153], v[182:185], v[44:47]
	v_mfma_f32_16x16x32_bf16 v[40:43], v[158:161], v[182:185], v[40:43]
	v_mfma_f32_16x16x32_bf16 v[28:31], v[150:153], v[174:177], v[28:31]
	v_mfma_f32_16x16x32_bf16 v[24:27], v[158:161], v[174:177], v[24:27]
	v_mfma_f32_16x16x32_bf16 v[12:15], v[150:153], v[166:169], v[12:15]
	v_mfma_f32_16x16x32_bf16 v[8:11], v[158:161], v[166:169], v[8:11]
	s_setprio 0
	s_setprio 1
	v_mfma_f32_16x16x32_bf16 v[52:55], v[130:133], v[186:189], v[52:55]
	v_mfma_f32_16x16x32_bf16 v[48:51], v[138:141], v[186:189], v[48:51]
	v_mfma_f32_16x16x32_bf16 v[36:39], v[130:133], v[178:181], v[36:39]
	v_mfma_f32_16x16x32_bf16 v[32:35], v[138:141], v[178:181], v[32:35]
	v_mfma_f32_16x16x32_bf16 v[20:23], v[130:133], v[170:173], v[20:23]
	v_mfma_f32_16x16x32_bf16 v[16:19], v[138:141], v[170:173], v[16:19]
	v_mfma_f32_16x16x32_bf16 v[4:7], v[130:133], v[162:165], v[4:7]
	v_mfma_f32_16x16x32_bf16 v[0:3], v[138:141], v[162:165], v[0:3]
	v_mfma_f32_16x16x32_bf16 v[52:55], v[134:137], v[190:193], v[52:55]
	v_mfma_f32_16x16x32_bf16 v[48:51], v[142:145], v[190:193], v[48:51]
	v_mfma_f32_16x16x32_bf16 v[36:39], v[134:137], v[182:185], v[36:39]
	v_mfma_f32_16x16x32_bf16 v[32:35], v[142:145], v[182:185], v[32:35]
	v_mfma_f32_16x16x32_bf16 v[20:23], v[134:137], v[174:177], v[20:23]
	v_mfma_f32_16x16x32_bf16 v[16:19], v[142:145], v[174:177], v[16:19]
	v_mfma_f32_16x16x32_bf16 v[4:7], v[134:137], v[166:169], v[4:7]
	v_mfma_f32_16x16x32_bf16 v[0:3], v[142:145], v[166:169], v[0:3]
	s_setprio 0
	s_branch .LBB0_412
